# XCD stagger in 4 groups of 2 XCDs (3us steps); rest as best
# baseline (speedup 1.0000x reference)
.LBB0_392:
	s_or_b64 exec, exec, s[0:1]
	v_mov_b32_e32 v0, 0
	s_add_u32 s98, s66, 0x40000
	s_addc_u32 s99, s67, 0
	s_nop 0
	global_load_dwordx4 v[4:7], v0, s[98:99] offset:32 sc1
	global_load_dwordx4 v[8:11], v0, s[98:99] offset:48 sc1
	s_mov_b32 s100, 1
	s_waitcnt vmcnt(0)
	v_readfirstlane_b32 s101, v4
	s_bcnt1_i32_b32 s101, s101
	s_cmp_eq_u32 s101, 1
	s_cselect_b32 s100, s100, 0
	v_readfirstlane_b32 s101, v5
	s_bcnt1_i32_b32 s101, s101
	s_cmp_eq_u32 s101, 1
	s_cselect_b32 s100, s100, 0
	v_readfirstlane_b32 s101, v6
	s_bcnt1_i32_b32 s101, s101
	s_cmp_eq_u32 s101, 1
	s_cselect_b32 s100, s100, 0
	v_readfirstlane_b32 s101, v7
	s_bcnt1_i32_b32 s101, s101
	s_cmp_eq_u32 s101, 1
	s_cselect_b32 s100, s100, 0
	v_readfirstlane_b32 s101, v8
	s_bcnt1_i32_b32 s101, s101
	s_cmp_eq_u32 s101, 1
	s_cselect_b32 s100, s100, 0
	v_readfirstlane_b32 s101, v9
	s_bcnt1_i32_b32 s101, s101
	s_cmp_eq_u32 s101, 1
	s_cselect_b32 s100, s100, 0
	v_readfirstlane_b32 s101, v10
	s_bcnt1_i32_b32 s101, s101
	s_cmp_eq_u32 s101, 1
	s_cselect_b32 s100, s100, 0
	v_readfirstlane_b32 s101, v11
	s_bcnt1_i32_b32 s101, s101
	s_cmp_eq_u32 s101, 1
	s_cselect_b32 s100, s100, 0
	v_writelane_b32 v255, s100, 0
	s_cmp_eq_u32 s100, 0
	s_cbranch_scc1 .Lxl_stag_done
	v_readlane_b32 s101, v254, 0
	s_nop 3
	s_lshr_b32 s101, s101, 1
	s_cmp_eq_u32 s101, 0
	s_cbranch_scc1 .Lxl_stag_done
